# pool mixer: rows of the next 64-token item requested one item ahead (software-pipelined staging)
# baseline (speedup 1.0000x reference)
.LBB0_320:
	v_readlane_b32 s2, v244, 31
	s_waitcnt vmcnt(0)
	s_cmpk_lt_i32 s2, 0x300
	s_cselect_b64 s[8:9], -1, 0
	v_readlane_b32 s72, v244, 32
	v_readlane_b32 s50, v244, 36
	v_readlane_b32 s70, v244, 2
	v_readlane_b32 s76, v244, 38
	v_mov_b32_e32 v55, v214
	s_and_b64 vcc, exec, s[8:9]
	v_readlane_b32 s49, v244, 28
	v_readlane_b32 s73, v244, 33
	v_readlane_b32 s74, v244, 34
	v_readlane_b32 s75, v244, 35
	v_readlane_b32 s51, v244, 37
	v_readlane_b32 s64, v244, 30
	v_readlane_b32 s65, v244, 29
	v_readlane_b32 s71, v244, 3
	v_readlane_b32 s77, v244, 39
	s_waitcnt vmcnt(0) lgkmcnt(0)
	s_barrier
	s_cbranch_vccz .LBB0_336
	v_bfe_u32 v34, v55, 4, 2
	s_lshl_b32 s0, s3, 12
	v_lshlrev_b32_e32 v0, 9, v34
	v_and_b32_e32 v35, 15, v55
	v_or3_b32 v0, s0, v0, v35
	v_lshlrev_b32_e32 v32, 2, v0
	v_mov_b32_e32 v33, 0
	v_lshl_add_u64 v[0:1], s[26:27], 0, v[32:33]
	v_add_co_u32_e32 v14, vcc, 0x2000, v0
	global_load_dword v0, v32, s[26:27] offset:448
	global_load_dword v2, v32, s[26:27] offset:192
	v_addc_co_u32_e32 v15, vcc, 0, v1, vcc
	global_load_dword v1, v[14:15], off offset:448
	global_load_dword v3, v[14:15], off offset:192
	global_load_dword v4, v[14:15], off offset:960
	global_load_dword v5, v[14:15], off offset:704
	global_load_dword v6, v[14:15], off offset:1472
	global_load_dword v7, v[14:15], off offset:1216
	global_load_dword v8, v[14:15], off offset:1984
	global_load_dword v9, v[14:15], off offset:1728
	global_load_dword v10, v32, s[26:27] offset:960
	global_load_dword v11, v32, s[26:27] offset:704
	global_load_dword v12, v32, s[26:27] offset:1472
	global_load_dword v13, v32, s[26:27] offset:1216
	global_load_dword v16, v32, s[26:27] offset:1984
	global_load_dword v17, v32, s[26:27] offset:1728
	global_load_dword v18, v[14:15], off offset:384
	global_load_dword v19, v[14:15], off offset:320
	global_load_dword v24, v[14:15], off offset:256
	global_load_dword v20, v[14:15], off offset:128
	global_load_dword v21, v32, s[26:27] offset:384
	global_load_dword v22, v32, s[26:27] offset:320
	global_load_dword v28, v32, s[26:27] offset:256
	global_load_dword v23, v32, s[26:27] offset:128
	global_load_dword v25, v[14:15], off offset:896
	global_load_dword v26, v[14:15], off offset:832
	global_load_dword v27, v[14:15], off offset:768
	global_load_dword v29, v[14:15], off offset:640
	global_load_dword v30, v32, s[26:27] offset:896
	global_load_dword v31, v32, s[26:27] offset:832
	global_load_dword v36, v32, s[26:27] offset:768
	global_load_dword v37, v32, s[26:27] offset:640
	global_load_dword v38, v[14:15], off offset:1408
	global_load_dword v39, v[14:15], off offset:1344
	global_load_dword v40, v[14:15], off offset:1280
	global_load_dword v41, v[14:15], off offset:1152
	global_load_dword v42, v32, s[26:27] offset:1408
	global_load_dword v43, v32, s[26:27] offset:1344
	global_load_dword v44, v32, s[26:27] offset:1280
	global_load_dword v45, v32, s[26:27] offset:1152
	global_load_dword v46, v[14:15], off offset:1920
	global_load_dword v47, v[14:15], off offset:1856
	global_load_dword v48, v[14:15], off offset:1792
	global_load_dword v49, v[14:15], off offset:1664
	global_load_dword v50, v32, s[26:27] offset:1920
	global_load_dword v51, v32, s[26:27] offset:1856
	global_load_dword v52, v32, s[26:27] offset:1792
	global_load_dword v53, v32, s[26:27] offset:1664
	s_movk_i32 s14, 0x7fff
	s_mov_b32 s15, 0xffff0000
	v_readlane_b32 s4, v244, 20
	s_movk_i32 s16, 0x210
	s_lshr_b32 s4, s4, 3
	s_and_b32 s4, s4, 0x1fffffe0
	s_lshl_b32 s6, s3, 7
	v_or_b32_e32 v83, s4, v35
	s_add_i32 s4, s6, 0
	s_movk_i32 s0, 0xa00
	v_or_b32_e32 v87, 16, v83
	v_cmp_gt_i32_e64 s[0:1], s0, v55
	v_lshlrev_b32_e32 v86, 4, v83
	v_lshlrev_b32_e32 v88, 4, v87
	s_movk_i32 s19, 0xf800
	s_movk_i32 s24, 0x800
	s_movk_i32 s25, 0x7ff
	v_mov_b32_e32 v91, 0x358637bd
	v_mov_b32_e32 v92, 0x260
	s_waitcnt vmcnt(43)
	v_bfe_u32 v57, v4, 16, 1
	s_waitcnt vmcnt(42)
	v_bfe_u32 v58, v5, 16, 1
	s_waitcnt vmcnt(41)
	v_bfe_u32 v59, v6, 16, 1
	s_waitcnt vmcnt(40)
	v_bfe_u32 v60, v7, 16, 1
	s_waitcnt vmcnt(39)
	v_bfe_u32 v61, v8, 16, 1
	s_waitcnt vmcnt(38)
	v_bfe_u32 v62, v9, 16, 1
	v_bfe_u32 v54, v0, 16, 1
	v_bfe_u32 v56, v2, 16, 1
	v_add3_u32 v54, v0, v54, s14
	v_add3_u32 v56, v2, v56, s14
	v_bfe_u32 v0, v1, 16, 1
	v_bfe_u32 v2, v3, 16, 1
	v_add3_u32 v0, v1, v0, s14
	v_add3_u32 v1, v3, v2, s14
	v_add3_u32 v3, v5, v58, s14
	v_add3_u32 v5, v7, v60, s14
	v_add3_u32 v2, v4, v57, s14
	v_add3_u32 v4, v6, v59, s14
	v_lshrrev_b32_e32 v1, 16, v1
	v_lshrrev_b32_e32 v3, 16, v3
	v_lshrrev_b32_e32 v5, 16, v5
	v_and_or_b32 v0, v0, s15, v1
	v_and_or_b32 v1, v2, s15, v3
	v_and_or_b32 v2, v4, s15, v5
	v_lshrrev_b32_e32 v4, 16, v56
	v_add3_u32 v7, v9, v62, s14
	v_and_or_b32 v4, v54, s15, v4
	global_load_dword v54, v[14:15], off offset:64
	v_add3_u32 v6, v8, v61, s14
	v_lshrrev_b32_e32 v7, 16, v7
	v_and_or_b32 v3, v6, s15, v7
	s_waitcnt vmcnt(37)
	v_bfe_u32 v6, v11, 16, 1
	global_load_dword v56, v[14:15], off offset:576
	global_load_dword v57, v[14:15], off offset:1088
	global_load_dword v58, v[14:15], off offset:1600
	v_bfe_u32 v5, v10, 16, 1
	v_add3_u32 v6, v11, v6, s14
	v_add3_u32 v5, v10, v5, s14
	v_lshrrev_b32_e32 v6, 16, v6
	s_waitcnt vmcnt(38)
	v_bfe_u32 v7, v13, 16, 1
	v_and_or_b32 v5, v5, s15, v6
	v_bfe_u32 v6, v12, 16, 1
	v_add3_u32 v7, v13, v7, s14
	v_add3_u32 v6, v12, v6, s14
	v_lshrrev_b32_e32 v7, 16, v7
	s_waitcnt vmcnt(36)
	v_bfe_u32 v8, v17, 16, 1
	v_and_or_b32 v6, v6, s15, v7
	v_bfe_u32 v7, v16, 16, 1
	v_add3_u32 v8, v17, v8, s14
	v_add3_u32 v7, v16, v7, s14
	v_lshrrev_b32_e32 v8, 16, v8
	s_waitcnt vmcnt(32)
	v_bfe_u32 v9, v20, 16, 1
	v_and_or_b32 v7, v7, s15, v8
	v_bfe_u32 v8, v18, 16, 1
	v_add3_u32 v9, v20, v9, s14
	v_add3_u32 v8, v18, v8, s14
	v_lshrrev_b32_e32 v9, 16, v9
	global_load_dword v20, v32, s[26:27] offset:64
	v_and_or_b32 v8, v8, s15, v9
	s_waitcnt vmcnt(28)
	v_bfe_u32 v9, v25, 16, 1
	v_add3_u32 v9, v25, v9, s14
	s_waitcnt vmcnt(25)
	v_bfe_u32 v10, v29, 16, 1
	global_load_dword v25, v32, s[26:27] offset:576
	v_add3_u32 v10, v29, v10, s14
	v_lshrrev_b32_e32 v10, 16, v10
	s_waitcnt vmcnt(18)
	v_bfe_u32 v11, v41, 16, 1
	global_load_dword v29, v32, s[26:27] offset:1088
	v_and_or_b32 v9, v9, s15, v10
	v_bfe_u32 v10, v38, 16, 1
	v_add3_u32 v11, v41, v11, s14
	v_add3_u32 v10, v38, v10, s14
	v_lshrrev_b32_e32 v11, 16, v11
	s_waitcnt vmcnt(11)
	v_bfe_u32 v12, v49, 16, 1
	global_load_dword v38, v32, s[26:27] offset:1600
	v_and_or_b32 v10, v10, s15, v11
	v_bfe_u32 v11, v46, 16, 1
	v_add3_u32 v12, v49, v12, s14
	v_add3_u32 v11, v46, v11, s14
	v_lshrrev_b32_e32 v12, 16, v12
	v_bfe_u32 v13, v23, 16, 1
	v_and_or_b32 v11, v11, s15, v12
	v_bfe_u32 v12, v21, 16, 1
	v_add3_u32 v13, v23, v13, s14
	v_add3_u32 v12, v21, v12, s14
	global_load_dword v41, v[14:15], off
	v_lshrrev_b32_e32 v13, 16, v13
	v_and_or_b32 v12, v12, s15, v13
	v_bfe_u32 v13, v30, 16, 1
	v_bfe_u32 v16, v37, 16, 1
	v_add3_u32 v13, v30, v13, s14
	v_add3_u32 v16, v37, v16, s14
	global_load_dword v37, v[14:15], off offset:1536
	global_load_dword v30, v[14:15], off offset:1024
	global_load_dword v46, v[14:15], off offset:512
	v_lshrrev_b32_e32 v16, 16, v16
	v_and_or_b32 v13, v13, s15, v16
	v_bfe_u32 v16, v42, 16, 1
	v_bfe_u32 v17, v45, 16, 1
	v_add3_u32 v16, v42, v16, s14
	v_add3_u32 v17, v45, v17, s14
	global_load_dword v49, v32, s[26:27] offset:1024
	global_load_dword v45, v32, s[26:27] offset:512
	global_load_dword v42, v32, s[26:27]
	v_lshrrev_b32_e32 v17, 16, v17
	global_load_dword v32, v32, s[26:27] offset:1536
	v_and_or_b32 v14, v16, s15, v17
	s_waitcnt vmcnt(16)
	v_bfe_u32 v16, v53, 16, 1
	v_bfe_u32 v15, v50, 16, 1
	v_add3_u32 v16, v53, v16, s14
	v_add3_u32 v15, v50, v15, s14
	v_lshrrev_b32_e32 v16, 16, v16
	s_waitcnt vmcnt(15)
	v_bfe_u32 v17, v54, 16, 1
	v_and_or_b32 v15, v15, s15, v16
	v_bfe_u32 v16, v19, 16, 1
	v_add3_u32 v17, v54, v17, s14
	v_add3_u32 v16, v19, v16, s14
	v_lshrrev_b32_e32 v17, 16, v17
	s_waitcnt vmcnt(14)
	v_bfe_u32 v18, v56, 16, 1
	v_and_or_b32 v16, v16, s15, v17
	v_bfe_u32 v17, v26, 16, 1
	v_add3_u32 v18, v56, v18, s14
	v_add3_u32 v17, v26, v17, s14
	v_lshrrev_b32_e32 v18, 16, v18
	s_waitcnt vmcnt(13)
	v_bfe_u32 v19, v57, 16, 1
	v_and_or_b32 v17, v17, s15, v18
	v_bfe_u32 v18, v39, 16, 1
	v_add3_u32 v19, v57, v19, s14
	v_add3_u32 v18, v39, v18, s14
	v_lshrrev_b32_e32 v19, 16, v19
	s_waitcnt vmcnt(12)
	v_bfe_u32 v21, v58, 16, 1
	v_and_or_b32 v18, v18, s15, v19
	v_bfe_u32 v19, v47, 16, 1
	v_add3_u32 v21, v58, v21, s14
	v_add3_u32 v19, v47, v19, s14
	v_lshrrev_b32_e32 v21, 16, v21
	v_and_or_b32 v19, v19, s15, v21
	v_bfe_u32 v21, v22, 16, 1
	v_add3_u32 v21, v22, v21, s14
	s_waitcnt vmcnt(11)
	v_bfe_u32 v22, v20, 16, 1
	v_add3_u32 v20, v20, v22, s14
	v_lshrrev_b32_e32 v20, 16, v20
	v_and_or_b32 v20, v21, s15, v20
	s_waitcnt vmcnt(10)
	v_bfe_u32 v22, v25, 16, 1
	v_bfe_u32 v21, v31, 16, 1
	v_add3_u32 v22, v25, v22, s14
	v_add3_u32 v21, v31, v21, s14
	v_lshrrev_b32_e32 v22, 16, v22
	s_waitcnt vmcnt(9)
	v_bfe_u32 v23, v29, 16, 1
	v_and_or_b32 v21, v21, s15, v22
	v_bfe_u32 v22, v43, 16, 1
	v_add3_u32 v23, v29, v23, s14
	v_add3_u32 v22, v43, v22, s14
	v_lshrrev_b32_e32 v23, 16, v23
	s_waitcnt vmcnt(8)
	v_bfe_u32 v25, v38, 16, 1
	v_and_or_b32 v22, v22, s15, v23
	v_bfe_u32 v23, v51, 16, 1
	v_add3_u32 v25, v38, v25, s14
	v_add3_u32 v23, v51, v23, s14
	v_lshrrev_b32_e32 v25, 16, v25
	v_and_or_b32 v23, v23, s15, v25
	v_bfe_u32 v25, v24, 16, 1
	v_add3_u32 v24, v24, v25, s14
	v_ashrrev_i32_e32 v57, 3, v55
	s_mov_b32 s26, 0xf800000
	s_waitcnt vmcnt(7)
	v_bfe_u32 v25, v41, 16, 1
	v_add3_u32 v25, v41, v25, s14
	v_lshrrev_b32_e32 v25, 16, v25
	v_and_or_b32 v24, v24, s15, v25
	v_bfe_u32 v25, v27, 16, 1
	v_add3_u32 v25, v27, v25, s14
	s_waitcnt vmcnt(6)
	v_bfe_u32 v29, v37, 16, 1
	s_waitcnt vmcnt(5)
	v_bfe_u32 v27, v30, 16, 1
	s_waitcnt vmcnt(4)
	v_bfe_u32 v26, v46, 16, 1
	v_add3_u32 v26, v46, v26, s14
	v_lshrrev_b32_e32 v26, 16, v26
	v_and_or_b32 v25, v25, s15, v26
	v_bfe_u32 v26, v40, 16, 1
	v_add3_u32 v27, v30, v27, s14
	v_add3_u32 v26, v40, v26, s14
	v_lshrrev_b32_e32 v27, 16, v27
	v_and_or_b32 v26, v26, s15, v27
	v_bfe_u32 v27, v48, 16, 1
	v_add3_u32 v29, v37, v29, s14
	v_add3_u32 v27, v48, v27, s14
	v_lshrrev_b32_e32 v29, 16, v29
	v_and_or_b32 v27, v27, s15, v29
	v_bfe_u32 v29, v28, 16, 1
	v_add3_u32 v28, v28, v29, s14
	s_waitcnt vmcnt(1)
	v_bfe_u32 v29, v42, 16, 1
	v_add3_u32 v29, v42, v29, s14
	v_lshrrev_b32_e32 v29, 16, v29
	v_bfe_u32 v30, v45, 16, 1
	v_and_or_b32 v28, v28, s15, v29
	v_bfe_u32 v29, v36, 16, 1
	v_add3_u32 v30, v45, v30, s14
	v_add3_u32 v29, v36, v29, s14
	v_lshrrev_b32_e32 v30, 16, v30
	v_bfe_u32 v31, v49, 16, 1
	v_and_or_b32 v29, v29, s15, v30
	v_bfe_u32 v30, v44, 16, 1
	v_add3_u32 v31, v49, v31, s14
	v_add3_u32 v30, v44, v30, s14
	v_lshrrev_b32_e32 v31, 16, v31
	s_waitcnt vmcnt(0)
	v_bfe_u32 v36, v32, 16, 1
	v_and_or_b32 v30, v30, s15, v31
	v_bfe_u32 v31, v52, 16, 1
	v_add3_u32 v32, v32, v36, s14
	v_add3_u32 v31, v52, v31, s14
	v_lshrrev_b32_e32 v32, 16, v32
	v_and_or_b32 v31, v31, s15, v32
	v_and_b32_e32 v32, 7, v55
	v_bfe_u32 v36, v55, 1, 2
	v_lshlrev_b32_e64 v82, v36, 1
	v_lshlrev_b32_e32 v36, 6, v32
	v_mul_lo_u32 v32, v57, s16
	v_add_u32_e32 v37, 0, v32
	v_lshlrev_b32_e32 v32, 4, v34
	v_add_u32_e32 v38, s4, v32
	s_lshl_b32 s4, s3, 8
	s_add_u32 s4, s28, s4
	s_addc_u32 s5, s29, 0
	v_lshl_add_u64 v[48:49], s[4:5], 0, v[32:33]
	v_mbcnt_hi_u32_b32 v32, -1, v215
	v_and_b32_e32 v39, 64, v32
	v_xor_b32_e32 v35, 16, v32
	v_add_u32_e32 v39, 64, v39
	v_cmp_lt_i32_e32 vcc, v35, v39
	s_lshl_b32 s3, s3, 2
	s_add_i32 s3, s3, 0
	v_cndmask_b32_e32 v35, v32, v35, vcc
	v_lshlrev_b32_e32 v84, 2, v35
	v_xor_b32_e32 v35, 32, v32
	v_cmp_lt_i32_e32 vcc, v35, v39
	s_add_i32 s3, s3, 0x12900
	s_add_u32 s6, s74, s6
	v_cndmask_b32_e32 v32, v32, v35, vcc
	v_lshlrev_b32_e32 v85, 2, v32
	s_addc_u32 s7, s75, 0
	v_lshlrev_b32_e32 v32, 3, v34
	v_cmp_eq_u32_e64 s[4:5], 0, v34
	v_lshl_add_u64 v[34:35], s[6:7], 0, v[32:33]
	s_mov_b64 s[6:7], 0x18800000
	v_lshl_add_u64 v[50:51], v[34:35], 0, s[6:7]
	v_lshlrev_b32_e32 v32, 4, v55
	v_readlane_b32 s6, v244, 24
	v_and_b32_e32 v32, 0x1f0, v32
	v_readlane_b32 s7, v244, 25
	v_add_u32_e32 v54, 0, v32
	s_lshl_b32 s17, s66, 6
	v_lshl_add_u64 v[52:53], s[6:7], 0, v[32:33]
	v_add_u32_e32 v33, 0, v36
	s_lshl_b32 s6, s2, 6
	v_mul_lo_u32 v32, v83, s16
	v_add_u32_e32 v56, 0x1080, v33
	v_add_u32_e32 v33, s6, v57
	v_sub_u32_e32 v89, v33, v82
	s_sub_i32 s18, 0, s6
	v_add_u32_e32 v90, v37, v36
	v_add_u32_e32 v93, v38, v32
	s_add_i32 s27, 0, 0x12900
	s_mov_b32 s28, s2
	s_lshl_b32 s98, s28, 6
	s_cmpk_lt_i32 s28, 0x100
	s_cselect_b32 s99, s19, 0x7fffc000
	s_cselect_b32 s100, s24, 0x4000
	s_and_b32 s99, s99, s98
	s_sub_i32 s98, s98, s99
	s_add_i32 s98, s98, -8
	v_ashrrev_i32_e32 v128, 5, v55
	v_add_u32_e32 v129, s98, v128
	v_mov_b32_e32 v131, v129
	v_cmp_gt_u32_e32 vcc, s100, v131
	v_add_u32_e32 v152, s99, v131
	v_ashrrev_i32_e32 v153, 31, v152
	v_lshlrev_b64 v[152:153], 9, v[152:153]
	v_lshl_add_u64 v[152:153], v[52:53], 0, v[152:153]
	s_and_saveexec_b64 s[12:13], vcc
	global_load_dwordx4 v[132:135], v[152:153], off
	s_or_b64 exec, exec, s[12:13]
	v_add_u32_e32 v131, 16, v129
	v_cmp_gt_u32_e32 vcc, s100, v131
	v_add_u32_e32 v152, s99, v131
	v_ashrrev_i32_e32 v153, 31, v152
	v_lshlrev_b64 v[152:153], 9, v[152:153]
	v_lshl_add_u64 v[152:153], v[52:53], 0, v[152:153]
	s_and_saveexec_b64 s[12:13], vcc
	global_load_dwordx4 v[136:139], v[152:153], off
	s_or_b64 exec, exec, s[12:13]
	v_add_u32_e32 v131, 32, v129
	v_cmp_gt_u32_e32 vcc, s100, v131
	v_add_u32_e32 v152, s99, v131
	v_ashrrev_i32_e32 v153, 31, v152
	v_lshlrev_b64 v[152:153], 9, v[152:153]
	v_lshl_add_u64 v[152:153], v[52:53], 0, v[152:153]
	s_and_saveexec_b64 s[12:13], vcc
	global_load_dwordx4 v[140:143], v[152:153], off
	s_or_b64 exec, exec, s[12:13]
	v_add_u32_e32 v131, 48, v129
	v_cmp_gt_u32_e32 vcc, s100, v131
	v_add_u32_e32 v152, s99, v131
	v_ashrrev_i32_e32 v153, 31, v152
	v_lshlrev_b64 v[152:153], 9, v[152:153]
	v_lshl_add_u64 v[152:153], v[52:53], 0, v[152:153]
	s_and_saveexec_b64 s[12:13], vcc
	global_load_dwordx4 v[144:147], v[152:153], off
	s_or_b64 exec, exec, s[12:13]
	v_add_u32_e32 v131, 64, v129
	v_cmp_gt_u32_e32 vcc, s100, v131
	v_add_u32_e32 v152, s99, v131
	v_ashrrev_i32_e32 v153, 31, v152
	v_lshlrev_b64 v[152:153], 9, v[152:153]
	v_lshl_add_u64 v[152:153], v[52:53], 0, v[152:153]
	s_and_saveexec_b64 s[12:13], vcc
	global_load_dwordx4 v[148:151], v[152:153], off
	s_or_b64 exec, exec, s[12:13]
	s_branch .LBB0_323

.LBB0_323:
	s_lshl_b32 s20, s28, 6
	s_cmpk_lt_i32 s28, 0x100
	s_cselect_b32 s6, s19, 0x7fffc000
	s_cselect_b32 s29, s24, 0x4000
	s_and_b32 s21, s6, s20
	s_sub_i32 s30, s20, s21
	s_and_saveexec_b64 s[6:7], s[0:1]
	s_cbranch_execz .LBB0_328
	s_add_i32 s31, s30, -8
	v_ashrrev_i32_e32 v128, 5, v55
	v_mad_u64_u32 v[38:39], s[34:35], v128, s16, v[54:55]
	v_add_u32_e32 v130, s31, v128
	s_waitcnt vmcnt(0)
	v_mov_b32_e32 v131, v130
	v_cmp_gt_u32_e32 vcc, s29, v131
	s_and_saveexec_b64 s[12:13], vcc
	ds_write_b128 v38, v[132:135] offset:0
	s_or_b64 exec, exec, s[12:13]
	v_add_u32_e32 v131, 16, v130
	v_cmp_gt_u32_e32 vcc, s29, v131
	s_and_saveexec_b64 s[12:13], vcc
	ds_write_b128 v38, v[136:139] offset:8448
	s_or_b64 exec, exec, s[12:13]
	v_add_u32_e32 v131, 32, v130
	v_cmp_gt_u32_e32 vcc, s29, v131
	s_and_saveexec_b64 s[12:13], vcc
	ds_write_b128 v38, v[140:143] offset:16896
	s_or_b64 exec, exec, s[12:13]
	v_add_u32_e32 v131, 48, v130
	v_cmp_gt_u32_e32 vcc, s29, v131
	s_and_saveexec_b64 s[12:13], vcc
	ds_write_b128 v38, v[144:147] offset:25344
	s_or_b64 exec, exec, s[12:13]
	v_add_u32_e32 v131, 64, v130
	v_cmp_gt_u32_e32 vcc, s29, v131
	s_and_saveexec_b64 s[12:13], vcc
	ds_write_b128 v38, v[148:151] offset:33792
	s_or_b64 exec, exec, s[12:13]
	s_add_i32 s101, s28, s66
	s_cmpk_gt_i32 s101, 0x2ff
	s_cbranch_scc1 .Lp2b_noreq
	s_lshl_b32 s98, s101, 6
	s_cmpk_lt_i32 s101, 0x100
	s_cselect_b32 s99, s19, 0x7fffc000
	s_cselect_b32 s100, s24, 0x4000
	s_and_b32 s99, s99, s98
	s_sub_i32 s98, s98, s99
	s_add_i32 s98, s98, -8
	s_nop 1
	v_ashrrev_i32_e32 v128, 5, v55
	v_add_u32_e32 v129, s98, v128
	v_mov_b32_e32 v131, v129
	v_cmp_gt_u32_e32 vcc, s100, v131
	v_add_u32_e32 v152, s99, v131
	v_ashrrev_i32_e32 v153, 31, v152
	v_lshlrev_b64 v[152:153], 9, v[152:153]
	v_lshl_add_u64 v[152:153], v[52:53], 0, v[152:153]
	s_and_saveexec_b64 s[12:13], vcc
	global_load_dwordx4 v[132:135], v[152:153], off
	s_or_b64 exec, exec, s[12:13]
	v_add_u32_e32 v131, 16, v129
	v_cmp_gt_u32_e32 vcc, s100, v131
	v_add_u32_e32 v152, s99, v131
	v_ashrrev_i32_e32 v153, 31, v152
	v_lshlrev_b64 v[152:153], 9, v[152:153]
	v_lshl_add_u64 v[152:153], v[52:53], 0, v[152:153]
	s_and_saveexec_b64 s[12:13], vcc
	global_load_dwordx4 v[136:139], v[152:153], off
	s_or_b64 exec, exec, s[12:13]
	v_add_u32_e32 v131, 32, v129
	v_cmp_gt_u32_e32 vcc, s100, v131
	v_add_u32_e32 v152, s99, v131
	v_ashrrev_i32_e32 v153, 31, v152
	v_lshlrev_b64 v[152:153], 9, v[152:153]
	v_lshl_add_u64 v[152:153], v[52:53], 0, v[152:153]
	s_and_saveexec_b64 s[12:13], vcc
	global_load_dwordx4 v[140:143], v[152:153], off
	s_or_b64 exec, exec, s[12:13]
	v_add_u32_e32 v131, 48, v129
	v_cmp_gt_u32_e32 vcc, s100, v131
	v_add_u32_e32 v152, s99, v131
	v_ashrrev_i32_e32 v153, 31, v152
	v_lshlrev_b64 v[152:153], 9, v[152:153]
	v_lshl_add_u64 v[152:153], v[52:53], 0, v[152:153]
	s_and_saveexec_b64 s[12:13], vcc
	global_load_dwordx4 v[144:147], v[152:153], off
	s_or_b64 exec, exec, s[12:13]
	v_add_u32_e32 v131, 64, v129
	v_cmp_gt_u32_e32 vcc, s100, v131
	v_add_u32_e32 v152, s99, v131
	v_ashrrev_i32_e32 v153, 31, v152
	v_lshlrev_b64 v[152:153], 9, v[152:153]
	v_lshl_add_u64 v[152:153], v[52:53], 0, v[152:153]
	s_and_saveexec_b64 s[12:13], vcc
	global_load_dwordx4 v[148:151], v[152:153], off
	s_or_b64 exec, exec, s[12:13]
.Lp2b_noreq:
.LBB0_328:
	s_or_b64 exec, exec, s[6:7]
	v_add_u32_e32 v32, s30, v57
	v_sub_u32_e32 v33, v32, v82
	v_add_u32_e32 v32, v32, v82
	v_max_i32_e32 v76, 0, v33
	v_min_i32_e32 v77, s29, v32
	v_mov_b32_e32 v33, 0
	v_cmp_gt_i32_e32 vcc, v77, v76
	v_mov_b32_e32 v32, v33
	v_mov_b32_e32 v35, v33
	v_mov_b32_e32 v34, v33
	v_mov_b32_e32 v37, v33
	v_mov_b32_e32 v36, v33
	v_mov_b32_e32 v39, v33
	v_mov_b32_e32 v38, v33
	v_mov_b32_e32 v41, v33
	v_mov_b32_e32 v40, v33
	v_mov_b32_e32 v43, v33
	v_mov_b32_e32 v42, v33
	v_mov_b32_e32 v45, v33
	v_mov_b32_e32 v44, v33
	v_mov_b32_e32 v47, v33
	v_mov_b32_e32 v46, v33
	v_mov_b32_e32 v59, v33
	v_mov_b32_e32 v58, v33
	v_mov_b32_e32 v61, v33
	v_mov_b32_e32 v60, v33
	v_mov_b32_e32 v63, v33
	v_mov_b32_e32 v62, v33
	v_mov_b32_e32 v65, v33
	v_mov_b32_e32 v64, v33
	v_mov_b32_e32 v67, v33
	v_mov_b32_e32 v66, v33
	v_mov_b32_e32 v69, v33
	v_mov_b32_e32 v68, v33
	v_mov_b32_e32 v71, v33
	v_mov_b32_e32 v70, v33
	v_mov_b32_e32 v73, v33
	v_mov_b32_e32 v72, v33
	s_waitcnt lgkmcnt(0)
	s_barrier
	s_and_saveexec_b64 s[6:7], vcc
	s_cbranch_execz .LBB0_332
	v_subrev_u32_e32 v32, s21, v89
	v_max_i32_e32 v32, 0, v32
	s_add_i32 s10, s18, s21
	v_add_u32_e32 v32, s10, v32
	v_mad_u64_u32 v[74:75], s[10:11], v32, s16, v[56:57]
	v_mov_b32_e32 v32, 0
	s_mov_b64 s[10:11], 0
	v_mov_b32_e32 v75, v76
	v_mov_b32_e32 v33, v32
	v_mov_b32_e32 v72, v32
	v_mov_b32_e32 v73, v32
	v_mov_b32_e32 v70, v32
	v_mov_b32_e32 v71, v32
	v_mov_b32_e32 v68, v32
	v_mov_b32_e32 v69, v32
	v_mov_b32_e32 v66, v32
	v_mov_b32_e32 v67, v32
	v_mov_b32_e32 v64, v32
	v_mov_b32_e32 v65, v32
	v_mov_b32_e32 v62, v32
	v_mov_b32_e32 v63, v32
	v_mov_b32_e32 v60, v32
	v_mov_b32_e32 v61, v32
	v_mov_b32_e32 v58, v32
	v_mov_b32_e32 v59, v32
	v_mov_b32_e32 v46, v32
	v_mov_b32_e32 v47, v32
	v_mov_b32_e32 v44, v32
	v_mov_b32_e32 v45, v32
	v_mov_b32_e32 v42, v32
	v_mov_b32_e32 v43, v32
	v_mov_b32_e32 v40, v32
	v_mov_b32_e32 v41, v32
	v_mov_b32_e32 v38, v32
	v_mov_b32_e32 v39, v32
	v_mov_b32_e32 v36, v32
	v_mov_b32_e32 v37, v32
	v_mov_b32_e32 v34, v32
	v_mov_b32_e32 v35, v32

	.amdhsa_kernel _Z9hymba_fwd4Args
		.amdhsa_group_segment_fixed_size 0
		.amdhsa_private_segment_fixed_size 0
		.amdhsa_kernarg_size 400
		.amdhsa_user_sgpr_count 2
		.amdhsa_user_sgpr_dispatch_ptr 0
		.amdhsa_user_sgpr_queue_ptr 0
		.amdhsa_user_sgpr_kernarg_segment_ptr 1
		.amdhsa_user_sgpr_dispatch_id 0
		.amdhsa_user_sgpr_kernarg_preload_length 0
		.amdhsa_user_sgpr_kernarg_preload_offset 0
		.amdhsa_user_sgpr_private_segment_size 0
		.amdhsa_uses_dynamic_stack 0
		.amdhsa_enable_private_segment 0
		.amdhsa_system_sgpr_workgroup_id_x 1
		.amdhsa_system_sgpr_workgroup_id_y 0
		.amdhsa_system_sgpr_workgroup_id_z 0
		.amdhsa_system_sgpr_workgroup_info 0
		.amdhsa_system_vgpr_workitem_id 2
		.amdhsa_next_free_vgpr 256
		.amdhsa_next_free_sgpr 102
		.amdhsa_accum_offset 256
		.amdhsa_reserve_vcc 1
		.amdhsa_float_round_mode_32 0
		.amdhsa_float_round_mode_16_64 0
		.amdhsa_float_denorm_mode_32 3
		.amdhsa_float_denorm_mode_16_64 3
		.amdhsa_dx10_clamp 1
		.amdhsa_ieee_mode 1
		.amdhsa_fp16_overflow 0
		.amdhsa_tg_split 0
		.amdhsa_exception_fp_ieee_invalid_op 0
		.amdhsa_exception_fp_denorm_src 0
		.amdhsa_exception_fp_ieee_div_zero 0
		.amdhsa_exception_fp_ieee_overflow 0
		.amdhsa_exception_fp_ieee_underflow 0
		.amdhsa_exception_fp_ieee_inexact 0
		.amdhsa_exception_int_div_zero 0
	.end_amdhsa_kernel

amdhsa.kernels:
  - .agpr_count:     0
    .args:
      - .offset:         0
        .size:           144
        .value_kind:     by_value
      - .offset:         144
        .size:           4
        .value_kind:     hidden_block_count_x
      - .offset:         148
        .size:           4
        .value_kind:     hidden_block_count_y
      - .offset:         152
        .size:           4
        .value_kind:     hidden_block_count_z
      - .offset:         156
        .size:           2
        .value_kind:     hidden_group_size_x
      - .offset:         158
        .size:           2
        .value_kind:     hidden_group_size_y
      - .offset:         160
        .size:           2
        .value_kind:     hidden_group_size_z
      - .offset:         162
        .size:           2
        .value_kind:     hidden_remainder_x
      - .offset:         164
        .size:           2
        .value_kind:     hidden_remainder_y
      - .offset:         166
        .size:           2
        .value_kind:     hidden_remainder_z
      - .offset:         184
        .size:           8
        .value_kind:     hidden_global_offset_x
      - .offset:         192
        .size:           8
        .value_kind:     hidden_global_offset_y
      - .offset:         200
        .size:           8
        .value_kind:     hidden_global_offset_z
      - .offset:         208
        .size:           2
        .value_kind:     hidden_grid_dims
      - .offset:         232
        .size:           8
        .value_kind:     hidden_multigrid_sync_arg
      - .offset:         264
        .size:           4
        .value_kind:     hidden_dynamic_lds_size
    .group_segment_fixed_size: 0
    .kernarg_segment_align: 8
    .kernarg_segment_size: 400
    .language:       OpenCL C
    .language_version:
      - 2
      - 0
    .max_flat_workgroup_size: 512
    .name:           _Z9hymba_fwd4Args
    .private_segment_fixed_size: 0
    .sgpr_count:     108
    .sgpr_spill_count: 63
    .symbol:         _Z9hymba_fwd4Args.kd
    .uniform_work_group_size: 1
    .uses_dynamic_stack: false
    .vgpr_count:     256
    .vgpr_spill_count: 0
    .wavefront_size: 64
